# prologues: stagger barrier of the second wave half moved behind its K-tile 1 DMA pieces (both halves have both K-tiles in flight from the start)
# baseline (speedup 1.0000x reference)
.LBB0_105:
	v_mov_b32_e32 v165, v27
	v_lshl_add_u64 v[58:59], s[86:87], 0, v[164:165]
	v_mov_b32_e32 v161, v27
	v_lshl_add_u64 v[84:85], s[86:87], 0, v[160:161]
	s_add_i32 m0, s17, 0x18000
	v_lshl_add_u64 v[58:59], v[58:59], 0, s[82:83]
	v_readlane_b32 s26, v251, 55
	v_mov_b32_e32 v167, v27
	global_load_lds_dwordx4 v[58:59], off
	v_lshl_add_u64 v[58:59], v[84:85], 0, s[82:83]
	s_add_i32 m0, s17, 0x1a000
	v_readlane_b32 s27, v251, 56
	s_add_i32 s22, s17, 0x8000
	v_mov_b32_e32 v163, v27
	global_load_lds_dwordx4 v[58:59], off
	v_lshl_add_u64 v[58:59], s[26:27], 0, v[166:167]
	s_mov_b32 m0, s22
	s_add_i32 s80, s17, 0xa000
	global_load_lds_dwordx4 v[58:59], off
	v_lshl_add_u64 v[58:59], s[26:27], 0, v[162:163]
	s_mov_b32 m0, s80
	s_and_b32 s1, s1, 3
	global_load_lds_dwordx4 v[58:59], off
	s_add_i32 m0, s17, 0x1c000
	v_lshl_add_u64 v[58:59], s[52:53], 0, v[164:165]
	global_load_lds_dwordx4 v[58:59], off
	v_lshl_add_u64 v[58:59], s[52:53], 0, v[160:161]
	s_add_i32 m0, s17, 0x1e000
	v_mul_lo_u32 v26, v26, s7
	global_load_lds_dwordx4 v[58:59], off
	s_cmp_lg_u32 s11, 1
	s_cbranch_scc1 .Lstg_6
	s_barrier
.Lstg_6:
	s_waitcnt vmcnt(8)
	s_barrier
	v_bfe_u32 v59, v37, 4, 2
	v_and_b32_e32 v58, 15, v37
	v_lshlrev_b32_e32 v185, 4, v59
	v_lshlrev_b32_e32 v37, 2, v37
	v_lshl_or_b32 v184, s11, 6, v58
	v_lshl_or_b32 v58, v58, 6, v185
	s_lshl_b32 s11, s11, 13
	v_and_b32_e32 v37, 32, v37
	v_bitop3_b32 v84, v58, s11, v37 bitop3:0xde
	s_lshl_b32 s11, s1, 12
	v_bitop3_b32 v186, v58, s11, v37 bitop3:0xde
	s_cmpk_lt_u32 s0, 0x100
	v_lshrrev_b32_e32 v37, 1, v56
	v_mul_lo_u32 v58, v39, s7
	s_mov_b32 s11, 0x2c000
	s_cselect_b64 s[60:61], -1, 0
	v_cmp_eq_u32_e64 s[38:39], 0, v59
	s_lshl_b32 s26, s1, 1
	v_lshl_or_b32 v187, s1, 6, v185
	v_mad_u64_u32 v[58:59], s[0:1], v37, s11, v[58:59]
	v_and_b32_e32 v37, 1, v56
	v_lshl_or_b32 v37, v37, 6, v58
	v_lshl_add_u32 v176, v57, 1, v37
	v_lshrrev_b32_e32 v37, 1, v36
	v_mad_u64_u32 v[56:57], s[0:1], v37, s11, v[26:27]
	s_waitcnt vmcnt(6)
	v_and_b32_e32 v26, 1, v36
	v_readlane_b32 s0, v251, 36
	v_lshl_or_b32 v26, v26, 6, v56
	s_mov_b32 s94, s0
	v_readlane_b32 s0, v251, 34
	v_readlane_b32 s78, v251, 37
	s_mov_b32 s81, 0
	s_orn2_b32 s26, s26, 47
	v_mov_b32_e32 v177, v27
	v_lshl_add_u32 v178, v38, 1, v26
	v_mov_b32_e32 v179, v27
	v_add_u32_e32 v188, 0, v84
	v_readlane_b32 s31, v251, 35
	s_mov_b32 s30, s0
	s_mov_b64 s[76:77], s[86:87]
	v_readlane_b32 s79, v251, 38
	s_barrier
	s_branch .LBB0_108

.LBB0_202:
	v_mov_b32_e32 v159, v27
	v_lshl_add_u64 v[10:11], s[36:37], 0, v[158:159]
	v_mov_b32_e32 v163, v27
	v_lshl_add_u64 v[12:13], s[36:37], 0, v[162:163]
	v_mov_b32_e32 v157, v27
	s_add_i32 m0, s11, 0x18000
	v_lshl_add_u64 v[10:11], v[10:11], 0, s[82:83]
	v_lshl_add_u64 v[14:15], s[70:71], 0, v[156:157]
	v_mov_b32_e32 v161, v27
	global_load_lds_dwordx4 v[10:11], off
	v_lshl_add_u64 v[10:11], v[12:13], 0, s[82:83]
	s_add_i32 m0, s11, 0x1a000
	s_add_i32 s26, s11, 0x8000
	v_lshl_add_u64 v[16:17], s[70:71], 0, v[160:161]
	global_load_lds_dwordx4 v[10:11], off
	v_lshl_add_u64 v[10:11], v[14:15], 0, s[82:83]
	s_mov_b32 m0, s26
	s_add_i32 s27, s11, 0xa000
	global_load_lds_dwordx4 v[10:11], off
	v_lshl_add_u64 v[10:11], v[16:17], 0, s[82:83]
	s_mov_b32 m0, s27
	v_and_b32_e32 v9, 15, v2
	global_load_lds_dwordx4 v[10:11], off
	s_add_i32 m0, s11, 0x1c000
	v_lshl_add_u64 v[10:11], s[28:29], 0, v[158:159]
	global_load_lds_dwordx4 v[10:11], off
	v_lshl_add_u64 v[10:11], s[28:29], 0, v[162:163]
	s_add_i32 m0, s11, 0x1e000
	v_and_b32_e32 v187, 48, v2
	global_load_lds_dwordx4 v[10:11], off
	s_cmp_lg_u32 s38, 1
	s_cbranch_scc1 .Lstg_5
	s_barrier
.Lstg_5:
	s_waitcnt vmcnt(8)
	s_barrier
	v_lshlrev_b32_e32 v10, 2, v2
	v_lshlrev_b32_e32 v2, 3, v2
	v_and_b32_e32 v164, 0x1f8, v2
	v_lshlrev_b32_e32 v2, 13, v3
	v_and_b32_e32 v2, 0xffffc000, v2
	v_lshl_add_u32 v2, v4, 10, v2
	v_and_b32_e32 v3, 1, v3
	s_and_b32 s39, s31, 3
	v_lshl_or_b32 v188, s38, 6, v9
	s_lshl_b32 s31, s38, 13
	v_lshl_or_b32 v9, v9, 6, v187
	v_and_b32_e32 v10, 32, v10
	v_lshl_or_b32 v2, v3, 6, v2
	v_bitop3_b32 v11, v9, s31, v10 bitop3:0xde
	s_lshl_b32 s31, s39, 12
	v_lshl_add_u32 v166, v5, 1, v2
	v_lshlrev_b32_e32 v2, 13, v6
	s_cmpk_lt_u32 s30, 0x100
	v_and_b32_e32 v2, 0xffffc000, v2
	v_bitop3_b32 v189, v9, s31, v10 bitop3:0xde
	s_waitcnt vmcnt(6)
	s_cselect_b64 s[30:31], -1, 0
	s_lshl_b32 s38, s38, 15
	s_lshl_b32 s39, s39, 13
	v_lshl_add_u32 v2, v7, 10, v2
	v_and_b32_e32 v3, 1, v6
	s_or_b32 s46, s39, s38
	v_lshl_or_b32 v2, v3, 6, v2
	v_readlane_b32 s4, v252, 16
	v_readlane_b32 s40, v250, 11
	s_ashr_i32 s47, s46, 31
	v_mov_b32_e32 v165, v27
	v_mov_b32_e32 v167, v27
	v_lshl_add_u32 v176, v8, 1, v2
	v_mov_b32_e32 v177, v27
	s_mov_b64 s[60:61], 0
	v_add_u32_e32 v190, 0, v11
	s_mov_b32 s58, s4
	v_readlane_b32 s41, v250, 12
	v_readlane_b32 s59, v252, 17
	s_mov_b64 s[78:79], s[70:71]
	s_mov_b64 s[76:77], s[36:37]
	s_barrier
	s_branch .LBB0_205

.LBB0_377:
	v_mov_b32_e32 v159, v27
	v_lshl_add_u64 v[2:3], s[20:21], 0, v[158:159]
	v_mov_b32_e32 v163, v27
	v_readlane_b32 s52, v253, 57
	v_lshl_add_u64 v[4:5], s[20:21], 0, v[162:163]
	v_mov_b32_e32 v157, v27
	v_readlane_b32 s53, v253, 58
	s_and_b32 s1, s1, 3
	s_add_i32 m0, s11, 0x18000
	v_lshl_add_u64 v[2:3], v[2:3], 0, s[82:83]
	v_lshl_add_u64 v[14:15], s[52:53], 0, v[156:157]
	v_mov_b32_e32 v161, v27
	s_lshl_b32 s12, s27, 13
	s_lshl_b32 s34, s1, 12
	global_load_lds_dwordx4 v[2:3], off
	v_lshl_add_u64 v[2:3], v[4:5], 0, s[82:83]
	s_add_i32 m0, s11, 0x1a000
	s_add_i32 s23, s11, 0x8000
	s_add_i32 s26, s11, 0xa000
	v_lshl_add_u64 v[16:17], s[52:53], 0, v[160:161]
	global_load_lds_dwordx4 v[2:3], off
	v_lshl_add_u64 v[2:3], v[14:15], 0, s[82:83]
	s_mov_b32 m0, s23
	s_add_u32 s30, s20, 0x20080
	global_load_lds_dwordx4 v[2:3], off
	v_lshl_add_u64 v[2:3], v[16:17], 0, s[82:83]
	s_mov_b32 m0, s26
	s_addc_u32 s31, s21, 0
	global_load_lds_dwordx4 v[2:3], off
	s_add_i32 m0, s11, 0x1c000
	v_lshl_add_u64 v[2:3], s[30:31], 0, v[158:159]
	global_load_lds_dwordx4 v[2:3], off
	v_lshl_add_u64 v[2:3], s[30:31], 0, v[162:163]
	s_add_i32 m0, s11, 0x1e000
	v_and_b32_e32 v188, 48, v6
	global_load_lds_dwordx4 v[2:3], off
	s_cmp_lg_u32 s27, 1
	s_cbranch_scc1 .Lstg_4
	s_barrier
.Lstg_4:
	s_waitcnt vmcnt(8)
	s_barrier
	v_and_b32_e32 v2, 15, v6
	v_lshlrev_b32_e32 v3, 2, v6
	v_lshl_or_b32 v189, s27, 6, v2
	v_lshl_or_b32 v2, v2, 6, v188
	v_and_b32_e32 v3, 32, v3
	v_bitop3_b32 v4, v2, s12, v3 bitop3:0xde
	v_bitop3_b32 v190, v2, s34, v3 bitop3:0xde
	v_lshlrev_b32_e32 v2, 3, v6
	v_and_b32_e32 v164, 0x1f8, v2
	v_lshlrev_b32_e32 v2, 13, v7
	v_and_b32_e32 v2, 0xffffc000, v2
	v_lshl_add_u32 v2, v8, 10, v2
	v_and_b32_e32 v3, 1, v7
	v_lshl_or_b32 v2, v3, 6, v2
	v_lshl_add_u32 v166, v9, 1, v2
	v_lshlrev_b32_e32 v2, 13, v10
	s_cmpk_lt_u32 s0, 0x100
	v_and_b32_e32 v2, 0xffffc000, v2
	s_waitcnt vmcnt(6)
	s_cselect_b64 s[30:31], -1, 0
	s_lshl_b32 s0, s27, 15
	s_lshl_b32 s1, s1, 13
	v_lshl_add_u32 v2, v11, 10, v2
	v_and_b32_e32 v3, 1, v10
	s_or_b32 s27, s1, s0
	v_lshl_or_b32 v2, v3, 6, v2
	v_readlane_b32 s0, v253, 51
	s_ashr_i32 s46, s27, 31
	v_mov_b32_e32 v165, v27
	v_mov_b32_e32 v167, v27
	v_lshl_add_u32 v176, v12, 1, v2
	v_mov_b32_e32 v177, v27
	s_mov_b64 s[36:37], -1
	v_add_u32_e32 v191, 0, v4
	s_mov_b32 s34, s0
	s_barrier
	s_branch .LBB0_380

.LBB0_491:
	v_lshl_add_u64 v[2:3], s[0:1], 0, v[26:27]
	v_mov_b32_e32 v161, v27
	v_and_b32_e32 v16, 15, v182
	v_and_b32_e32 v184, 48, v182
	v_lshlrev_b32_e32 v17, 2, v182
	v_lshl_add_u64 v[4:5], s[0:1], 0, v[160:161]
	v_mov_b32_e32 v157, v27
	s_and_b32 s27, s20, 3
	v_lshl_or_b32 v185, s11, 6, v16
	s_lshl_b32 s12, s11, 13
	v_lshl_or_b32 v16, v16, 6, v184
	v_and_b32_e32 v17, 32, v17
	s_add_i32 m0, s17, 0x18000
	v_lshl_add_u64 v[2:3], v[2:3], 0, s[82:83]
	v_lshl_add_u64 v[12:13], s[84:85], 0, v[156:157]
	v_mov_b32_e32 v159, v27
	v_bitop3_b32 v18, v16, s12, v17 bitop3:0xde
	s_lshl_b32 s12, s27, 12
	global_load_lds_dwordx4 v[2:3], off
	v_lshl_add_u64 v[2:3], v[4:5], 0, s[82:83]
	s_add_i32 m0, s17, 0x1a000
	s_add_i32 s34, s17, 0x8000
	s_add_i32 s35, s17, 0xa000
	v_lshl_add_u64 v[14:15], s[84:85], 0, v[158:159]
	global_load_lds_dwordx4 v[2:3], off
	v_lshl_add_u64 v[2:3], v[12:13], 0, s[82:83]
	s_mov_b32 m0, s34
	s_add_u32 s20, s0, 0x20080
	global_load_lds_dwordx4 v[2:3], off
	v_lshl_add_u64 v[2:3], v[14:15], 0, s[82:83]
	s_mov_b32 m0, s35
	s_addc_u32 s21, s1, 0
	global_load_lds_dwordx4 v[2:3], off
	s_add_i32 m0, s17, 0x1c000
	v_lshl_add_u64 v[2:3], s[20:21], 0, v[26:27]
	global_load_lds_dwordx4 v[2:3], off
	v_lshl_add_u64 v[2:3], s[20:21], 0, v[160:161]
	s_add_i32 m0, s17, 0x1e000
	v_readlane_b32 s4, v251, 61
	global_load_lds_dwordx4 v[2:3], off
	s_cmp_lg_u32 s11, 1
	s_cbranch_scc1 .Lstg_3
	s_barrier
.Lstg_3:
	s_waitcnt vmcnt(8)
	s_barrier
	v_lshlrev_b32_e32 v2, 13, v6
	v_and_b32_e32 v2, 0xffffc000, v2
	v_lshl_add_u32 v2, v7, 10, v2
	v_and_b32_e32 v3, 1, v6
	v_lshl_or_b32 v2, v3, 6, v2
	v_lshl_add_u32 v2, v8, 1, v2
	v_mov_b32_e32 v3, v27
	v_readlane_b32 s5, v251, 62
	s_waitcnt vmcnt(6)
	v_bitop3_b32 v186, v16, s12, v17 bitop3:0xde
	s_mov_b32 s36, -2
	v_lshl_add_u64 v[162:163], s[4:5], 0, v[2:3]
	v_lshlrev_b32_e32 v2, 13, v9
	v_and_b32_e32 v2, 0xffffc000, v2
	v_lshl_add_u32 v2, v10, 10, v2
	v_and_b32_e32 v3, 1, v9
	v_lshl_or_b32 v2, v3, 6, v2
	v_lshl_add_u32 v2, v11, 1, v2
	v_mov_b32_e32 v3, v27
	v_lshl_add_u64 v[164:165], s[4:5], 0, v[2:3]
	s_mov_b64 s[20:21], 0xd220080
	v_add_u32_e32 v187, 0, v18
	s_barrier

.LBB0_542:
	s_and_b32 s1, s1, 3
	s_add_i32 m0, s16, 0x18000
	v_lshl_add_u64 v[146:147], v[146:147], 0, s[82:83]
	s_lshl_b32 s12, s34, 13
	s_lshl_b32 s35, s1, 12
	global_load_lds_dwordx4 v[146:147], off
	v_lshl_add_u64 v[144:145], v[144:145], 0, s[82:83]
	s_add_i32 m0, s16, 0x1a000
	s_add_i32 s26, s16, 0x8000
	s_add_i32 s27, s16, 0xa000
	global_load_lds_dwordx4 v[144:145], off
	v_lshl_add_u64 v[140:141], v[140:141], 0, s[82:83]
	s_mov_b32 m0, s26
	s_add_u32 s30, s58, 0x60080
	global_load_lds_dwordx4 v[140:141], off
	v_lshl_add_u64 v[140:141], v[142:143], 0, s[82:83]
	s_mov_b32 m0, s27
	s_addc_u32 s31, s59, 0
	global_load_lds_dwordx4 v[140:141], off
	s_add_i32 m0, s16, 0x1c000
	v_lshl_add_u64 v[140:141], s[30:31], 0, v[134:135]
	global_load_lds_dwordx4 v[140:141], off
	v_lshl_add_u64 v[140:141], s[30:31], 0, v[138:139]
	s_add_i32 m0, s16, 0x1e000
	v_lshlrev_b32_e32 v144, 2, v149
	global_load_lds_dwordx4 v[140:141], off
	s_cmp_lg_u32 s34, 1
	s_cbranch_scc1 .Lstg_2
	s_barrier
.Lstg_2:
	s_waitcnt vmcnt(8)
	s_barrier
	v_bfe_u32 v141, v149, 4, 2
	v_and_b32_e32 v140, 15, v149
	v_lshlrev_b32_e32 v142, 4, v141
	v_lshl_or_b32 v143, v140, 6, v142
	v_and_b32_e32 v144, 32, v144
	s_cmpk_lt_u32 s0, 0x100
	v_bitop3_b32 v146, v143, s12, v144 bitop3:0xde
	s_cselect_b64 s[30:31], -1, 0
	s_lshl_b32 s0, s34, 15
	s_lshl_b32 s12, s1, 13
	v_lshl_or_b32 v228, s1, 6, v142
	v_lshrrev_b32_e32 v142, 1, v148
	v_mul_lo_u32 v26, v26, s7
	s_mov_b32 s4, 0x2c000
	v_bitop3_b32 v227, v143, s35, v144 bitop3:0xde
	s_or_b32 s46, s12, s0
	v_mad_u64_u32 v[142:143], s[0:1], v142, s4, v[26:27]
	v_and_b32_e32 v26, 1, v148
	v_lshl_or_b32 v26, v26, 6, v142
	v_lshl_add_u32 v142, v150, 1, v26
	v_lshrrev_b32_e32 v144, 1, v151
	v_mul_lo_u32 v26, v152, s7
	s_waitcnt vmcnt(6)
	v_mad_u64_u32 v[144:145], s[0:1], v144, s4, v[26:27]
	v_and_b32_e32 v26, 1, v151
	v_lshl_or_b32 v226, s34, 6, v140
	v_lshlrev_b32_e32 v140, 3, v140
	v_lshl_or_b32 v26, v26, 6, v144
	s_ashr_i32 s47, s46, 31
	v_lshl_or_b32 v140, v141, 7, v140
	v_mov_b32_e32 v141, v27
	s_mul_hi_i32 s68, s13, 0x160000
	s_mul_i32 s74, s13, 0x160000
	s_mul_hi_i32 s75, s56, 0x60000
	s_mul_i32 s76, s56, 0x60000
	v_mov_b32_e32 v143, v27
	v_lshl_add_u32 v144, v153, 1, v26
	v_mov_b32_e32 v145, v27
	s_mov_b32 s0, 0
	v_add_u32_e32 v229, 0, v146
	s_mov_b32 s79, 0
	s_barrier
	s_branch .LBB0_545

.LBB0_668:
	s_and_b32 s12, s1, 3
	s_add_i32 m0, s11, 0x18000
	v_lshl_add_u64 v[138:139], v[138:139], 0, s[82:83]
	s_lshl_b32 s1, s30, 13
	s_lshl_b32 s31, s12, 12
	global_load_lds_dwordx4 v[138:139], off
	v_lshl_add_u64 v[136:137], v[136:137], 0, s[82:83]
	s_add_i32 m0, s11, 0x1a000
	s_add_i32 s46, s11, 0x8000
	s_add_i32 s47, s11, 0xa000
	global_load_lds_dwordx4 v[136:137], off
	v_lshl_add_u64 v[132:133], v[132:133], 0, s[82:83]
	s_mov_b32 m0, s46
	s_add_u32 s26, s74, 0x40080
	global_load_lds_dwordx4 v[132:133], off
	v_lshl_add_u64 v[132:133], v[134:135], 0, s[82:83]
	s_mov_b32 m0, s47
	s_addc_u32 s27, s75, 0
	global_load_lds_dwordx4 v[132:133], off
	s_add_i32 m0, s11, 0x1c000
	v_lshl_add_u64 v[132:133], s[26:27], 0, v[178:179]
	global_load_lds_dwordx4 v[132:133], off
	v_lshl_add_u64 v[132:133], s[26:27], 0, v[182:183]
	s_add_i32 m0, s11, 0x1e000
	v_lshlrev_b32_e32 v135, 2, v140
	global_load_lds_dwordx4 v[132:133], off
	s_cmp_lg_u32 s30, 1
	s_cbranch_scc1 .Lstg_1
	s_barrier
.Lstg_1:
	s_waitcnt vmcnt(8)
	s_barrier
	v_bfe_u32 v133, v140, 4, 2
	v_and_b32_e32 v132, 15, v140
	v_lshlrev_b32_e32 v201, 4, v133
	v_lshl_or_b32 v200, s30, 6, v132
	v_lshl_or_b32 v132, v132, 6, v201
	v_and_b32_e32 v135, 32, v135
	v_bitop3_b32 v136, v132, s1, v135 bitop3:0xde
	v_bitop3_b32 v202, v132, s31, v135 bitop3:0xde
	v_lshrrev_b32_e32 v132, 1, v141
	v_mul_lo_u32 v26, v26, s7
	s_mov_b32 s5, 0x2c000
	v_lshlrev_b32_e32 v134, 3, v133
	s_cmpk_lt_u32 s0, 0x100
	v_cmp_eq_u32_e64 s[0:1], 0, v133
	v_mad_u64_u32 v[132:133], s[34:35], v132, s5, v[26:27]
	v_and_b32_e32 v26, 1, v141
	v_lshl_or_b32 v26, v26, 6, v132
	v_lshl_add_u32 v188, v142, 1, v26
	v_lshrrev_b32_e32 v132, 1, v143
	v_mul_lo_u32 v26, v144, s7
	s_waitcnt vmcnt(6)
	s_cselect_b64 s[26:27], -1, 0
	v_lshl_or_b32 v203, s12, 5, v134
	s_or_b32 s30, s12, s30
	v_mad_u64_u32 v[132:133], s[34:35], v132, s5, v[26:27]
	v_and_b32_e32 v26, 1, v143
	s_cmp_eq_u32 s30, 0
	v_lshlrev_b32_e32 v184, 2, v203
	v_mov_b32_e32 v185, v27
	v_lshl_or_b32 v26, v26, 6, v132
	s_mov_b32 s57, 0
	s_cselect_b64 s[30:31], -1, 0
	v_lshl_add_u64 v[186:187], s[48:49], 0, v[184:185]
	v_mov_b32_e32 v189, v27
	v_lshl_add_u32 v190, v145, 1, v26
	v_mov_b32_e32 v191, v27
	v_add_u32_e32 v185, 0, v136
	s_lshl_b32 s68, s12, 2
	s_barrier
	s_branch .LBB0_671

.LBB0_727:
	s_and_b32 s12, s1, 3
	s_add_i32 m0, s11, 0x18000
	v_lshl_add_u64 v[138:139], v[138:139], 0, s[82:83]
	s_lshl_b32 s1, s26, 13
	s_lshl_b32 s27, s12, 12
	global_load_lds_dwordx4 v[138:139], off
	v_lshl_add_u64 v[136:137], v[136:137], 0, s[82:83]
	s_add_i32 m0, s11, 0x1a000
	s_add_i32 s46, s11, 0x8000
	s_add_i32 s47, s11, 0xa000
	global_load_lds_dwordx4 v[136:137], off
	v_lshl_add_u64 v[132:133], v[132:133], 0, s[82:83]
	s_mov_b32 m0, s46
	s_add_u32 s30, s58, 0x40080
	global_load_lds_dwordx4 v[132:133], off
	v_lshl_add_u64 v[132:133], v[134:135], 0, s[82:83]
	s_mov_b32 m0, s47
	s_addc_u32 s31, s59, 0
	global_load_lds_dwordx4 v[132:133], off
	s_add_i32 m0, s11, 0x1c000
	v_lshl_add_u64 v[132:133], s[30:31], 0, v[146:147]
	global_load_lds_dwordx4 v[132:133], off
	v_lshl_add_u64 v[132:133], s[30:31], 0, v[150:151]
	s_add_i32 m0, s11, 0x1e000
	v_mul_lo_u32 v26, v26, s7
	global_load_lds_dwordx4 v[132:133], off
	s_cmp_lg_u32 s26, 1
	s_cbranch_scc1 .Lstg_0
	s_barrier
.Lstg_0:
	s_waitcnt vmcnt(8)
	s_barrier
	v_bfe_u32 v133, v140, 4, 2
	v_and_b32_e32 v132, 15, v140
	v_lshlrev_b32_e32 v135, 4, v133
	v_lshl_or_b32 v164, s26, 6, v132
	v_lshl_or_b32 v132, v132, 6, v135
	v_lshlrev_b32_e32 v135, 2, v140
	v_and_b32_e32 v135, 32, v135
	v_bitop3_b32 v136, v132, s1, v135 bitop3:0xde
	v_bitop3_b32 v165, v132, s27, v135 bitop3:0xde
	v_lshrrev_b32_e32 v132, 1, v141
	s_mov_b32 s4, 0x2c000
	v_lshlrev_b32_e32 v134, 3, v133
	s_cmpk_lt_u32 s0, 0x100
	v_cmp_eq_u32_e64 s[0:1], 0, v133
	v_mad_u64_u32 v[132:133], s[30:31], v132, s4, v[26:27]
	v_and_b32_e32 v26, 1, v141
	v_lshl_or_b32 v26, v26, 6, v132
	v_lshl_add_u32 v152, v142, 1, v26
	v_lshrrev_b32_e32 v132, 1, v143
	v_mul_lo_u32 v26, v154, s7
	s_waitcnt vmcnt(6)
	v_mad_u64_u32 v[132:133], s[30:31], v132, s4, v[26:27]
	v_and_b32_e32 v26, 1, v143
	v_lshl_or_b32 v26, v26, 6, v132
	s_cselect_b64 s[26:27], -1, 0
	v_lshl_or_b32 v166, s12, 5, v134
	s_mov_b32 s57, 0
	v_mov_b32_e32 v153, v27
	v_lshl_add_u32 v154, v155, 1, v26
	v_mov_b32_e32 v155, v27
	v_add_u32_e32 v167, 0, v136
	s_lshl_b32 s68, s12, 2
	s_barrier
	s_branch .LBB0_730
